# attention tile code outside the flash loops raised to priority 3 (above the MFMA clusters at 2, softmax 0)
# baseline (speedup 1.0000x reference)
; __device__ __forceinline__ void nsa_tile(const Params& p, int qb, int bg, char* smem) {
;     int tid = threadIdx.x; asm volatile("" : "+v"(tid));
;     const int lane = tid & 63, w = tid >> 6, fr = lane & 15, fq = lane >> 4;
;     const int b = bg >> 2, g = bg & 3, t0 = qb * 32, hq = g * 4 + w;
;     const bf16_t* projA = (const bf16_t*)(p.ws + OFF_PROJA);
;     const bf16_t* projVT = (const bf16_t*)(p.ws + OFF_PROJVT);
;     float* part = (float*)(smem + 36864);
;     u64* selmask = (u64*)(smem + 69632);
;     bf16x8 qf[2][2];
;     int tpos[2];
;     float glog[2][3];
;     ...
;     const bf16_t* qbase = projA + (size_t)(b * S + t0) * LDA;
; #pragma unroll
;     for (int qt = 0; qt < 2; ++qt) {
;         tpos[qt] = t0 + qt * 16 + fr;
;         const bf16_t* qrow = qbase + (size_t)(qt * 16 + fr) * LDA;
; #pragma unroll
;         for (int ks = 0; ks < 2; ++ks) qf[qt][ks] = *(const bf16x8*)(qrow + hq * 64 + ks * 32 + fq * 8);
; #pragma unroll
;         for (int br = 0; br < 3; ++br) glog[qt][br] = __uint_as_float(((unsigned)qrow[2048 + hq * 3 + br]) << 16);
;     }
;     f32x4 outacc[2][4];
;     {
;         const bf16_t* kcg = (const bf16_t*)(p.ws + OFF_KC) + (size_t)bg * 256 * 64;
;         const int nkp0 = (qb >> 4) + 1;
;         for (int i = 0; i < nkp0; ++i) {
;             const int q = w + 4 * i, row = q * 8 + (lane >> 3), cp = lane & 7;
;             const int f = ((row >> 1) & 1) | (((row >> 3) & 1) << 1) | (((row >> 4) & 1) << 2);
;             __builtin_amdgcn_global_load_lds((const unsigned*)(kcg + row * 64 + (cp ^ f) * 8), (__attribute__((address_space(3))) unsigned*)(smem + q * 1024), 16, 0, 0);
;         }
; __global__ void __launch_bounds__(256, 2) fwd_megakernel(Params p) {
;     ...
;     for (int r = 0; r * G < 4096; ++r) {
;         const int k = (r & 1) ? (G - 1 - (int)blockIdx.x) : (int)blockIdx.x, i = r * G + k;
;         if (i < 4096) nsa_tile(p, 127 - (i >> 5), i & 31, smem);
.LBB0_340:
	s_setprio 3
	s_bitcmp0_b32 s3, 0
	v_readlane_b32 s1, v245, 0
	v_readlane_b32 s2, v245, 62
	s_cselect_b32 s1, s1, s2
	s_add_i32 s0, s1, s0
	s_cmpk_gt_i32 s0, 0xfff
	s_cbranch_scc1 .LBB0_339
	v_writelane_b32 v244, s3, 11
	s_ashr_i32 s2, s0, 5
	s_and_b32 s3, s0, 31
	v_mov_b32_e32 v76, v114
	s_bfe_u32 s1, s0, 0x30002
	s_and_b32 s0, s0, 3
	s_sub_i32 s6, 0x7f, s2
	v_writelane_b32 v244, s0, 12
	v_ashrrev_i32_e32 v80, 6, v76
	s_lshl_b32 s13, s6, 5
	v_lshl_add_u32 v0, s0, 2, v80
	v_writelane_b32 v244, s1, 13
	s_lshl_b32 s0, s1, 12
	v_writelane_b32 v244, s0, 14
	s_add_i32 s0, s0, s13
	s_waitcnt vmcnt(0)
	v_and_b32_e32 v30, 15, v76
	s_mul_hi_u32 s1, s0, 0x1100
	s_mulk_i32 s0, 0x1100
	v_readlane_b32 s4, v245, 55
	v_readlane_b32 s5, v245, 56
	s_add_u32 s0, s4, s0
	v_lshlrev_b32_e32 v2, 6, v0
	v_lshl_add_u32 v4, v0, 1, v0
	v_mul_u32_u24_e32 v0, 0x880, v30
	s_addc_u32 s1, s5, s1
	v_ashrrev_i32_e32 v3, 31, v2
	v_lshlrev_b32_e32 v0, 1, v0
	v_ashrrev_i32_e32 v5, 31, v4
	v_lshl_add_u64 v[12:13], s[0:1], 0, v[0:1]
	v_lshlrev_b64 v[88:89], 1, v[2:3]
	v_lshlrev_b64 v[16:17], 1, v[4:5]
	v_lshl_add_u64 v[2:3], v[12:13], 0, v[88:89]
	v_and_b32_e32 v0, 48, v76
	s_mov_b64 s[0:1], 0x11000
	v_lshl_add_u64 v[18:19], v[16:17], 0, s[18:19]
	v_lshl_add_u64 v[2:3], v[2:3], 0, v[0:1]
	v_lshl_add_u64 v[20:21], v[12:13], 0, s[0:1]
	global_load_dwordx4 v[4:7], v[2:3], off
	global_load_dwordx4 v[8:11], v[2:3], off offset:64
	v_lshl_add_u64 v[2:3], v[12:13], 0, v[18:19]
	v_lshl_add_u64 v[12:13], v[20:21], 0, v[88:89]
	v_lshl_add_u64 v[16:17], v[20:21], 0, v[16:17]
	s_movk_i32 s0, 0x1000
	v_lshl_add_u64 v[22:23], v[12:13], 0, v[0:1]
	global_load_dword v120, v[2:3], off
	global_load_ushort v91, v[2:3], off offset:4
	global_load_dwordx4 v[12:15], v[22:23], off
	v_lshl_add_u64 v[2:3], v[20:21], 0, v[18:19]
	v_add_co_u32_e32 v20, vcc, s0, v16
	s_lshl_b32 s16, s3, 15
	s_nop 0
	v_addc_co_u32_e32 v21, vcc, 0, v17, vcc
	global_load_dwordx4 v[16:19], v[22:23], off offset:64
	global_load_ushort v82, v[2:3], off
	global_load_dword v111, v[20:21], off offset:2
	v_readlane_b32 s1, v245, 63
	v_lshlrev_b32_e32 v3, 1, v80
	s_add_u32 s4, s1, s16
	v_readlane_b32 s1, v244, 0
	v_and_b32_e32 v0, 7, v76
	v_bfe_u32 v2, v76, 4, 1
	v_and_b32_e32 v3, 6, v3
	s_addc_u32 s5, s1, 0
	s_lshr_b32 s3, s6, 4
	v_bitop3_b32 v0, v3, v0, v2 bitop3:0x36
	v_lshlrev_b32_e32 v20, 3, v76
	v_lshlrev_b32_e32 v0, 4, v0
	s_add_i32 s8, s3, 1
	s_mov_b32 s0, 0
	v_and_b32_e32 v22, 0x1c0, v20
	s_cmpk_lt_u32 s6, 0x70
	v_lshl_add_u64 v[2:3], s[4:5], 0, v[0:1]
	v_writelane_b32 v244, s6, 15
	s_cbranch_scc1 .LBB0_344
	v_lshl_or_b32 v20, v80, 9, v22
	s_and_b32 s0, s8, 0x1ffffff8
	v_lshl_add_u32 v0, v80, 10, v87
	v_add_u32_e32 v20, 0x3800, v20
	s_mov_b32 s1, 0

; __device__ __forceinline__ unsigned cvt_pk_bf16(float lo, float hi) { const f32x2_t f = {lo, hi}; return __builtin_bit_cast(unsigned, __builtin_convertvector(f, bf16x2_t)); }
; __device__ __forceinline__ f32x4 mfma16(bf16x8 a, bf16x8 b, f32x4 c) { return __builtin_amdgcn_mfma_f32_16x16x32_bf16(a, b, c, 0, 0, 0); }
; template <int KW, int VD, bool SEL> ...
;     ...
;                 for (int jj = 0; jj < 4; ++jj) { s[qt][tt][jj] = __builtin_amdgcn_exp2f(s[qt][tt][jj]); ps += s[qt][tt][jj]; }
;             lrow[qt] += ps;
; #pragma unroll
;             for (int i = 0; i < 2; ++i) {
;                 u32x4 pk;
;                 pk.x = cvt_pk_bf16(s[qt][2 * i][0], s[qt][2 * i][1]); pk.y = cvt_pk_bf16(s[qt][2 * i][2], s[qt][2 * i][3]);
;                 pk.z = cvt_pk_bf16(s[qt][2 * i + 1][0], s[qt][2 * i + 1][1]); pk.w = cvt_pk_bf16(s[qt][2 * i + 1][2], s[qt][2 * i + 1][3]);
;                 pf[qt][i] = __builtin_bit_cast(bf16x8, pk);
;             }
;         }
; #pragma unroll
;         for (int i = 0; i < 2; ++i) {
; #pragma unroll
;             for (int dt = 0; dt < VD / 16; ++dt) {
;                 const bf16x8 vf = *(const bf16x8*)(sV + (dt * 16 + fr) * 128 + ((i * 4 + fq) ^ vswz) * 16);
;                 O[0][dt] = mfma16(vf, pf[0][i], O[0][dt]);
;                 O[1][dt] = mfma16(vf, pf[1][i], O[1][dt]);
;             }
;         }
;         asm volatile("s_waitcnt vmcnt(0)" ::: "memory");
;         __syncthreads();
;         if (jn < 0) break;
;         j = jn; cur ^= 1;
;     }
;     ...
; #pragma unroll
;     for (int qt = 0; qt < 2; ++qt) { lrow[qt] += __shfl_xor(lrow[qt], 16); lrow[qt] += __shfl_xor(lrow[qt], 32); }
.LBB0_385:
	v_exp_f32_e32 v2, v80
	v_exp_f32_e32 v3, v81
	v_exp_f32_e32 v80, v82
	v_exp_f32_e32 v81, v83
	v_add_f32_e32 v82, 0, v2
	v_exp_f32_e32 v72, v72
	v_add_f32_e32 v82, v3, v82
	v_exp_f32_e32 v73, v73
	v_add_f32_e32 v82, v80, v82
	v_exp_f32_e32 v74, v74
	v_add_f32_e32 v82, v81, v82
	v_exp_f32_e32 v75, v75
	v_add_f32_e32 v82, v72, v82
	v_exp_f32_e32 v76, v76
	v_add_f32_e32 v82, v73, v82
	v_exp_f32_e32 v77, v77
	v_add_f32_e32 v82, v74, v82
	v_exp_f32_e32 v78, v78
	v_add_f32_e32 v82, v75, v82
	v_exp_f32_e32 v79, v79
	v_add_f32_e32 v82, v76, v82
	v_exp_f32_e32 v83, v68
	v_exp_f32_e32 v106, v69
	v_cvt_pk_bf16_f32 v69, v80, v81
	v_add_u32_e32 v80, s12, v128
	v_add_f32_e32 v82, v77, v82
	v_add_u32_e32 v81, v80, v125
	v_add_f32_e32 v82, v78, v82
	v_exp_f32_e32 v107, v70
	v_exp_f32_e32 v131, v71
	v_cvt_pk_bf16_f32 v70, v72, v73
	v_cvt_pk_bf16_f32 v71, v74, v75
	ds_read_b128 v[72:75], v81 offset:8192
	v_add_f32_e32 v68, v79, v82
	v_add_f32_e32 v68, v83, v68
	v_exp_f32_e32 v143, v60
	v_exp_f32_e32 v144, v61
	v_exp_f32_e32 v145, v62
	v_exp_f32_e32 v162, v63
	ds_read_b128 v[60:63], v81 offset:10240
	v_add_f32_e32 v68, v106, v68
	v_add_f32_e32 v82, v107, v68
	v_cvt_pk_bf16_f32 v68, v2, v3
	v_exp_f32_e32 v2, v56
	v_exp_f32_e32 v3, v57
	v_exp_f32_e32 v141, v58
	v_exp_f32_e32 v142, v59
	v_cvt_pk_bf16_f32 v58, v143, v144
	v_cvt_pk_bf16_f32 v56, v2, v3
	v_cvt_pk_bf16_f32 v59, v145, v162
	v_cvt_pk_bf16_f32 v57, v141, v142
	s_waitcnt lgkmcnt(1)
	s_setprio 2
	v_mfma_f32_16x16x32_bf16 v[48:51], v[72:75], v[68:71], v[48:51]
	v_cvt_pk_bf16_f32 v76, v76, v77
	v_cvt_pk_bf16_f32 v77, v78, v79
	v_cvt_pk_bf16_f32 v78, v83, v106
	v_mfma_f32_16x16x32_bf16 v[32:35], v[72:75], v[56:59], v[32:35]
	v_add_f32_e32 v72, v131, v82
	v_add_f32_e32 v105, v105, v72
	ds_read_b128 v[72:75], v81 offset:12288
	s_waitcnt lgkmcnt(1)
	v_mfma_f32_16x16x32_bf16 v[44:47], v[60:63], v[68:71], v[44:47]
	v_exp_f32_e32 v82, v53
	v_exp_f32_e32 v83, v54
	v_exp_f32_e32 v64, v64
	v_mfma_f32_16x16x32_bf16 v[28:31], v[60:63], v[56:59], v[28:31]
	ds_read_b128 v[60:63], v81 offset:14336
	v_exp_f32_e32 v81, v52
	v_exp_f32_e32 v65, v65
	s_waitcnt lgkmcnt(1)
	v_mfma_f32_16x16x32_bf16 v[40:43], v[72:75], v[68:71], v[40:43]
	v_exp_f32_e32 v66, v66
	v_exp_f32_e32 v67, v67
	v_add_f32_e32 v2, 0, v2
	v_mfma_f32_16x16x32_bf16 v[24:27], v[72:75], v[56:59], v[24:27]
	v_add_u32_e32 v73, v80, v126
	v_exp_f32_e32 v72, v55
	ds_read_b128 v[52:55], v73 offset:8192
	s_waitcnt lgkmcnt(1)
	v_mfma_f32_16x16x32_bf16 v[36:39], v[60:63], v[68:71], v[36:39]
	v_add_f32_e32 v2, v3, v2
	v_add_f32_e32 v2, v141, v2
	v_cvt_pk_bf16_f32 v79, v107, v131
	v_mfma_f32_16x16x32_bf16 v[20:23], v[60:63], v[56:59], v[20:23]
	ds_read_b128 v[60:63], v73 offset:10240
	v_cvt_pk_bf16_f32 v56, v81, v82
	v_cvt_pk_bf16_f32 v57, v83, v72
	v_cvt_pk_bf16_f32 v58, v64, v65
	v_cvt_pk_bf16_f32 v59, v66, v67
	v_add_f32_e32 v2, v142, v2
	s_waitcnt lgkmcnt(1)
	v_mfma_f32_16x16x32_bf16 v[48:51], v[52:55], v[76:79], v[48:51]
	v_add_f32_e32 v2, v143, v2
	v_add_f32_e32 v2, v144, v2
	v_add_f32_e32 v2, v145, v2
	v_mfma_f32_16x16x32_bf16 v[32:35], v[52:55], v[56:59], v[32:35]
	ds_read_b128 v[52:55], v73 offset:12288
	v_add_f32_e32 v2, v162, v2
	v_add_f32_e32 v2, v81, v2
	s_waitcnt lgkmcnt(1)
	v_mfma_f32_16x16x32_bf16 v[44:47], v[60:63], v[76:79], v[44:47]
	v_add_f32_e32 v2, v82, v2
	v_add_f32_e32 v2, v83, v2
	v_add_f32_e32 v2, v72, v2
	v_mfma_f32_16x16x32_bf16 v[28:31], v[60:63], v[56:59], v[28:31]
	ds_read_b128 v[60:63], v73 offset:14336
	v_add_f32_e32 v2, v64, v2
	v_add_f32_e32 v2, v65, v2
	s_waitcnt lgkmcnt(1)
	v_mfma_f32_16x16x32_bf16 v[40:43], v[52:55], v[76:79], v[40:43]
	v_add_f32_e32 v2, v66, v2
	s_waitcnt vmcnt(0)
	v_add_f32_e32 v2, v67, v2
	v_mfma_f32_16x16x32_bf16 v[24:27], v[52:55], v[56:59], v[24:27]
	s_xor_b32 s10, s10, 1
	v_add_f32_e32 v104, v104, v2
	s_cmp_gt_i32 s11, -1
	s_waitcnt lgkmcnt(0)
	v_mfma_f32_16x16x32_bf16 v[36:39], v[60:63], v[76:79], v[36:39]
	s_barrier
	v_mfma_f32_16x16x32_bf16 v[20:23], v[60:63], v[56:59], v[20:23]
	s_setprio 0
	s_cbranch_scc1 .LBB0_369
	s_setprio 3
	ds_bpermute_b32 v3, v119, v105
	ds_bpermute_b32 v2, v119, v104
	s_waitcnt lgkmcnt(0)
	v_pk_add_f32 v[2:3], v[104:105], v[2:3]
	ds_bpermute_b32 v53, v118, v3
	ds_bpermute_b32 v52, v118, v2
	s_waitcnt lgkmcnt(0)
	v_pk_add_f32 v[2:3], v[2:3], v[52:53]
	s_branch .LBB0_388

; __device__ __forceinline__ unsigned cvt_pk_bf16(float lo, float hi) { const f32x2_t f = {lo, hi}; return __builtin_bit_cast(unsigned, __builtin_convertvector(f, bf16x2_t)); }
; __device__ __forceinline__ f32x4 mfma16(bf16x8 a, bf16x8 b, f32x4 c) { return __builtin_amdgcn_mfma_f32_16x16x32_bf16(a, b, c, 0, 0, 0); }
; template <int KW, int VD, bool SEL> ...
;     ...
;                 for (int jj = 0; jj < 4; ++jj) { s[qt][tt][jj] = __builtin_amdgcn_exp2f(s[qt][tt][jj]); ps += s[qt][tt][jj]; }
;             lrow[qt] += ps;
; #pragma unroll
;             for (int i = 0; i < 2; ++i) {
;                 u32x4 pk;
;                 pk.x = cvt_pk_bf16(s[qt][2 * i][0], s[qt][2 * i][1]); pk.y = cvt_pk_bf16(s[qt][2 * i][2], s[qt][2 * i][3]);
;                 pk.z = cvt_pk_bf16(s[qt][2 * i + 1][0], s[qt][2 * i + 1][1]); pk.w = cvt_pk_bf16(s[qt][2 * i + 1][2], s[qt][2 * i + 1][3]);
;                 pf[qt][i] = __builtin_bit_cast(bf16x8, pk);
;             }
;         }
; #pragma unroll
;         for (int i = 0; i < 2; ++i) {
; #pragma unroll
;             for (int dt = 0; dt < VD / 16; ++dt) {
;                 const bf16x8 vf = *(const bf16x8*)(sV + (dt * 16 + fr) * 128 + ((i * 4 + fq) ^ vswz) * 16);
;                 O[0][dt] = mfma16(vf, pf[0][i], O[0][dt]);
;                 O[1][dt] = mfma16(vf, pf[1][i], O[1][dt]);
;             }
;         }
;         asm volatile("s_waitcnt vmcnt(0)" ::: "memory");
;         __syncthreads();
;         if (jn < 0) break;
;         j = jn; cur ^= 1;
;     }
;     ...
; #pragma unroll
;     for (int qt = 0; qt < 2; ++qt) { lrow[qt] += __shfl_xor(lrow[qt], 16); lrow[qt] += __shfl_xor(lrow[qt], 32); }
.LBB0_406:
	v_exp_f32_e32 v2, v80
	v_exp_f32_e32 v3, v81
	v_exp_f32_e32 v80, v82
	v_exp_f32_e32 v81, v83
	v_add_f32_e32 v82, 0, v2
	v_exp_f32_e32 v83, v68
	v_add_f32_e32 v82, v3, v82
	v_exp_f32_e32 v129, v69
	v_add_f32_e32 v82, v80, v82
	v_exp_f32_e32 v130, v70
	v_add_f32_e32 v68, v81, v82
	v_exp_f32_e32 v71, v71
	v_add_f32_e32 v68, v83, v68
	v_exp_f32_e32 v82, v72
	v_add_f32_e32 v68, v129, v68
	v_exp_f32_e32 v131, v73
	v_add_f32_e32 v68, v130, v68
	v_exp_f32_e32 v141, v74
	v_add_f32_e32 v68, v71, v68
	v_exp_f32_e32 v142, v75
	v_add_f32_e32 v68, v82, v68
	v_exp_f32_e32 v143, v76
	v_cvt_pk_bf16_f32 v69, v80, v81
	v_add_u32_e32 v80, s13, v126
	v_add_f32_e32 v68, v131, v68
	v_exp_f32_e32 v144, v77
	v_add_u32_e32 v81, v80, v123
	v_add_f32_e32 v68, v141, v68
	v_exp_f32_e32 v145, v78
	ds_read_b128 v[72:75], v81 offset:8192
	v_add_f32_e32 v68, v142, v68
	v_add_f32_e32 v68, v143, v68
	v_cvt_pk_bf16_f32 v71, v130, v71
	v_exp_f32_e32 v130, v60
	v_exp_f32_e32 v162, v61
	v_exp_f32_e32 v163, v62
	v_exp_f32_e32 v164, v63
	ds_read_b128 v[60:63], v81 offset:10240
	v_add_f32_e32 v68, v144, v68
	v_add_f32_e32 v76, v145, v68
	v_cvt_pk_bf16_f32 v68, v2, v3
	v_cvt_pk_bf16_f32 v70, v83, v129
	v_exp_f32_e32 v2, v56
	v_exp_f32_e32 v3, v57
	v_exp_f32_e32 v83, v58
	v_exp_f32_e32 v129, v59
	v_exp_f32_e32 v79, v79
	v_cvt_pk_bf16_f32 v56, v2, v3
	v_cvt_pk_bf16_f32 v58, v130, v162
	v_cvt_pk_bf16_f32 v57, v83, v129
	v_cvt_pk_bf16_f32 v59, v163, v164
	s_waitcnt lgkmcnt(1)
	s_setprio 2
	v_mfma_f32_16x16x32_bf16 v[48:51], v[72:75], v[68:71], v[48:51]
	v_exp_f32_e32 v64, v64
	v_exp_f32_e32 v65, v65
	v_exp_f32_e32 v66, v66
	v_mfma_f32_16x16x32_bf16 v[32:35], v[72:75], v[56:59], v[32:35]
	v_add_f32_e32 v72, v79, v76
	v_add_f32_e32 v105, v105, v72
	ds_read_b128 v[72:75], v81 offset:12288
	s_waitcnt lgkmcnt(1)
	v_mfma_f32_16x16x32_bf16 v[44:47], v[60:63], v[68:71], v[44:47]
	v_cvt_pk_bf16_f32 v76, v82, v131
	v_exp_f32_e32 v82, v53
	v_exp_f32_e32 v131, v54
	v_mfma_f32_16x16x32_bf16 v[28:31], v[60:63], v[56:59], v[28:31]
	ds_read_b128 v[60:63], v81 offset:14336
	v_exp_f32_e32 v81, v52
	v_exp_f32_e32 v67, v67
	s_waitcnt lgkmcnt(1)
	v_mfma_f32_16x16x32_bf16 v[40:43], v[72:75], v[68:71], v[40:43]
	v_add_f32_e32 v2, 0, v2
	v_add_f32_e32 v2, v3, v2
	v_add_f32_e32 v2, v83, v2
	v_mfma_f32_16x16x32_bf16 v[24:27], v[72:75], v[56:59], v[24:27]
	v_add_u32_e32 v73, v80, v124
	v_exp_f32_e32 v72, v55
	ds_read_b128 v[52:55], v73 offset:8192
	s_waitcnt lgkmcnt(1)
	v_mfma_f32_16x16x32_bf16 v[36:39], v[60:63], v[68:71], v[36:39]
	v_cvt_pk_bf16_f32 v77, v141, v142
	v_cvt_pk_bf16_f32 v78, v143, v144
	v_cvt_pk_bf16_f32 v79, v145, v79
	v_mfma_f32_16x16x32_bf16 v[20:23], v[60:63], v[56:59], v[20:23]
	ds_read_b128 v[60:63], v73 offset:10240
	v_cvt_pk_bf16_f32 v56, v81, v82
	v_cvt_pk_bf16_f32 v57, v131, v72
	v_cvt_pk_bf16_f32 v58, v64, v65
	v_cvt_pk_bf16_f32 v59, v66, v67
	v_add_f32_e32 v2, v129, v2
	s_waitcnt lgkmcnt(1)
	v_mfma_f32_16x16x32_bf16 v[48:51], v[52:55], v[76:79], v[48:51]
	v_add_f32_e32 v2, v130, v2
	v_add_f32_e32 v2, v162, v2
	v_add_f32_e32 v2, v163, v2
	v_mfma_f32_16x16x32_bf16 v[32:35], v[52:55], v[56:59], v[32:35]
	ds_read_b128 v[52:55], v73 offset:12288
	v_add_f32_e32 v2, v164, v2
	v_add_f32_e32 v2, v81, v2
	s_waitcnt lgkmcnt(1)
	v_mfma_f32_16x16x32_bf16 v[44:47], v[60:63], v[76:79], v[44:47]
	v_add_f32_e32 v2, v82, v2
	v_add_f32_e32 v2, v131, v2
	v_add_f32_e32 v2, v72, v2
	v_mfma_f32_16x16x32_bf16 v[28:31], v[60:63], v[56:59], v[28:31]
	ds_read_b128 v[60:63], v73 offset:14336
	v_add_f32_e32 v2, v64, v2
	v_add_f32_e32 v2, v65, v2
	s_waitcnt lgkmcnt(1)
	v_mfma_f32_16x16x32_bf16 v[40:43], v[52:55], v[76:79], v[40:43]
	v_add_f32_e32 v2, v66, v2
	s_waitcnt vmcnt(0)
	v_add_f32_e32 v2, v67, v2
	v_mfma_f32_16x16x32_bf16 v[24:27], v[52:55], v[56:59], v[24:27]
	s_xor_b32 s11, s11, 1
	v_add_f32_e32 v104, v104, v2
	s_cmp_gt_i32 s12, -1
	s_waitcnt lgkmcnt(0)
	v_mfma_f32_16x16x32_bf16 v[36:39], v[60:63], v[76:79], v[36:39]
	s_barrier
	v_mfma_f32_16x16x32_bf16 v[20:23], v[60:63], v[56:59], v[20:23]
	s_setprio 0
	s_cbranch_scc1 .LBB0_390
	s_setprio 3
	ds_bpermute_b32 v3, v119, v105
	ds_bpermute_b32 v2, v119, v104
	s_waitcnt lgkmcnt(0)
	v_pk_add_f32 v[2:3], v[104:105], v[2:3]
	ds_bpermute_b32 v5, v118, v3
	ds_bpermute_b32 v4, v118, v2
	s_waitcnt lgkmcnt(0)
	v_pk_add_f32 v[2:3], v[2:3], v[4:5]
	s_branch .LBB0_338

; template <int KW, int VD, bool SEL> ...
;     ...
;     if (!tiles) return;
;     int koff[NKI], voff[NVI];
; #pragma unroll
;     for (int i = 0; i < NKI; ++i) {
;         const int row = (w + 4 * i) * KRPI + lane / KCPR, cp = lane % KCPR;
;         const int f = (KW == 64) ? (((row >> 1) & 1) | (((row >> 3) & 1) << 1) | (((row >> 4) & 1) << 2)) : ((row & 3) | (((row >> 3) & 3) << 2));
;         koff[i] = row * ldk + (cp ^ f) * 8;
;     }
; #pragma unroll
;     for (int i = 0; i < NVI; ++i) {
;         const int row = (w + 4 * i) * 8 + (lane >> 3), cp = lane & 7;
;         voff[i] = row * S + (cp ^ ((row >> 1) & 7)) * 8;
;     }
; __device__ __forceinline__ void diff_tile(const Params& p, int qb, int bh, float lam, char* smem) {
;     int tid = threadIdx.x; asm volatile("" : "+v"(tid));
;     const int lane = tid & 63, w = tid >> 6, fr = lane & 15, fq = lane >> 4;
;     const int b = bh >> 3, h = bh & 7, map = w >> 1, half = w & 1, tw0 = qb * 64 + half * 32;
;     const bf16_t* projA = (const bf16_t*)(p.ws + OFF_PROJA);
;     const bf16_t* projVT = (const bf16_t*)(p.ws + OFF_PROJVT);
;     bf16x8 qf[2][2];
;     int tpos[2];
; #pragma unroll
;     for (int qt = 0; qt < 2; ++qt) {
;         tpos[qt] = tw0 + qt * 16 + fr;
;         const bf16_t* qrow = projA + (size_t)(b * S + tpos[qt]) * LDA + (h * 2 + map) * 64;
; #pragma unroll
;         for (int ks = 0; ks < 2; ++ks) qf[qt][ks] = *(const bf16x8*)(qrow + ks * 32 + fq * 8);
;     }
;     f32x4 O[2][8];
; #pragma unroll
;     for (int qt = 0; qt < 2; ++qt)
; #pragma unroll
;         for (int dt = 0; dt < 8; ++dt) O[qt][dt] = zero4();
;     float mr[2] = {-1e30f, -1e30f}, lr[2] = {0.f, 0.f};
;     const int lo[2] = {-1, -1};
;     const u64 ones[2] = {~0ull, ~0ull};
;     const u64 tiles = (qb == 63) ? ~0ull : ((1ull << (qb + 1)) - 1ull);
;     flash_branch<128, 128, false>(tiles, projA + (size_t)b * S * LDA + 1024 + h * 128, LDA, projVT + ((size_t)b * 1024 + h * 128) * S, map * 64,
;                                   qf, O, mr, lr, tpos, ones, lo, qb * 64, -1, smem);
; __global__ void __launch_bounds__(256, 2) fwd_megakernel(Params p) {
;     ...
;         for (int r = 0; r * G < 4096; ++r) {
;             const int k = (r & 1) ? (G - 1 - (int)blockIdx.x) : (int)blockIdx.x, i = r * G + k;
;             if (i < 4096) diff_tile(p, 63 - (i >> 6), i & 63, lam, smem);
.LBB0_817:
	s_setprio 3
	s_bitcmp0_b32 s17, 0
	v_readlane_b32 s7, v245, 0
	v_readlane_b32 s8, v245, 62
	s_cselect_b32 s7, s7, s8
	s_add_i32 s6, s7, s6
	s_cmpk_gt_i32 s6, 0xfff
	s_cbranch_scc1 .LBB0_816
	v_mov_b32_e32 v172, v114
	s_lshl_b32 s9, s6, 7
	s_and_b32 s18, s9, 0x380
	v_and_b32_e32 v0, 15, v172
	v_ashrrev_i32_e32 v173, 7, v172
	v_lshrrev_b32_e32 v1, 1, v172
	s_and_b32 s7, s6, 0xffffffc0
	v_and_or_b32 v171, v1, 32, v0
	v_lshl_add_u32 v0, v173, 6, s18
	v_readlane_b32 s20, v245, 55
	v_bfe_u32 v170, v172, 4, 2
	s_sub_i32 s19, 0xfc0, s7
	v_ashrrev_i32_e32 v1, 31, v0
	v_readlane_b32 s21, v245, 56
	s_bfe_u32 s8, s6, 0x30003
	v_or_b32_e32 v127, s19, v171
	v_lshl_add_u64 v[0:1], v[0:1], 1, s[20:21]
	v_lshlrev_b32_e32 v124, 4, v170
	v_mov_b32_e32 v125, v119
	s_lshl_b32 s7, s8, 12
	v_lshl_add_u64 v[0:1], v[0:1], 0, v[124:125]
	v_or_b32_e32 v125, 16, v127
	v_add_u32_e32 v118, s7, v127
	v_add_u32_e32 v126, s7, v125
	v_mad_u64_u32 v[2:3], s[10:11], v118, s3, v[0:1]
	v_mad_u64_u32 v[0:1], s[10:11], v126, s3, v[0:1]
	global_load_dwordx4 v[64:67], v[2:3], off
	global_load_dwordx4 v[68:71], v[2:3], off offset:64
	global_load_dwordx4 v[72:75], v[0:1], off
	global_load_dwordx4 v[76:79], v[0:1], off offset:64
	s_ashr_i32 s7, s6, 6
	s_sub_i32 s7, 64, s7
	s_lshl_b64 s[10:11], -1, s7
	s_not_b64 s[10:11], s[10:11]
	s_cmp_gt_u32 s6, 63
	s_cselect_b32 s7, s11, -1
	s_cselect_b32 s6, s10, -1
	v_mov_b32_e32 v0, v114
	s_cmp_eq_u64 s[6:7], 0
	s_cbranch_scc1 .LBB0_838
	v_ashrrev_i32_e32 v2, 6, v0
	v_bfe_u32 v1, v0, 4, 2
	v_lshlrev_b32_e32 v3, 2, v2
	v_lshlrev_b32_e32 v6, 1, v2
	v_and_b32_e32 v4, 15, v0
	v_or_b32_e32 v5, v3, v1
	v_and_b32_e32 v6, 12, v6
	s_mul_i32 s9, s8, 0x1100000
	v_mul_lo_u32 v5, v5, s12
	v_bitop3_b32 v6, v6, v4, v1 bitop3:0x36
	s_add_u32 s9, s20, s9
	v_lshl_or_b32 v128, v6, 3, v5
	v_add_u32_e32 v5, 16, v3
	s_addc_u32 s10, s21, 0
	s_lshl_b32 s11, s18, 1
	v_or_b32_e32 v6, v5, v1
	v_lshrrev_b32_e32 v5, 1, v5
	s_add_u32 s20, s9, s11
	v_and_b32_e32 v5, 12, v5
	s_addc_u32 s21, s10, 0
	s_lshl_b32 s8, s8, 23
	v_readlane_b32 s9, v245, 57
	v_mul_lo_u32 v6, v6, s12
	v_bitop3_b32 v5, v5, v4, v1 bitop3:0x36
	v_add_u32_e32 v3, 48, v3
	s_add_u32 s8, s9, s8
	v_readlane_b32 s9, v245, 58
	v_lshl_or_b32 v130, v5, 3, v6
	v_or_b32_e32 v5, v3, v1
	v_lshrrev_b32_e32 v3, 1, v3
	s_addc_u32 s9, s9, 0
	s_lshl_b32 s10, s18, 13
	v_and_b32_e32 v3, 12, v3
	s_add_u32 s22, s8, s10
	v_mul_lo_u32 v5, v5, s12
	v_bitop3_b32 v3, v3, v4, v1 bitop3:0x36
	s_addc_u32 s23, s9, 0
	v_lshl_or_b32 v134, v3, 3, v5
	v_bfe_u32 v3, v0, 3, 3
	v_lshl_or_b32 v3, v2, 3, v3
	s_ff1_i32_b64 s10, s[6:7]
	s_add_u32 s8, s6, -1
	v_lshlrev_b32_e32 v5, 12, v3
	v_lshrrev_b32_e32 v3, 1, v3
	s_addc_u32 s9, s7, -1
	s_mul_i32 s11, s10, 0x44000
	v_xor_b32_e32 v3, v3, v0
	s_add_u32 s24, s20, s11
	v_lshlrev_b32_e32 v3, 3, v3
	v_lshlrev_b32_e32 v174, 10, v2
	s_addc_u32 s25, s21, 0
	v_ashrrev_i32_e32 v129, 31, v128
	v_and_or_b32 v136, v3, 56, v5
	v_lshl_add_u64 v[2:3], v[128:129], 1, s[24:25]
	v_readfirstlane_b32 s26, v174
	v_lshl_add_u64 v[2:3], v[2:3], 0, s[0:1]
	s_mov_b32 m0, s26
	v_ashrrev_i32_e32 v131, 31, v130
	v_add_u32_e32 v5, 0x1000, v174
	v_add_u32_e32 v132, 0x11000, v128
	global_load_lds_dwordx4 v[2:3], off
	v_lshl_add_u64 v[2:3], v[130:131], 1, s[24:25]
	v_readfirstlane_b32 s26, v5
	v_lshl_add_u64 v[2:3], v[2:3], 0, s[0:1]
	s_mov_b32 m0, s26
	v_ashrrev_i32_e32 v133, 31, v132
	v_add_u32_e32 v5, 0x2000, v174
	global_load_lds_dwordx4 v[2:3], off
	v_lshl_add_u64 v[2:3], v[132:133], 1, s[24:25]
	v_readfirstlane_b32 s26, v5
	v_lshl_add_u64 v[2:3], v[2:3], 0, s[0:1]
	s_mov_b32 m0, s26
	v_ashrrev_i32_e32 v135, 31, v134
	v_add_u32_e32 v5, 0x3000, v174
	s_lshl_b32 s11, s10, 7
	global_load_lds_dwordx4 v[2:3], off
	v_lshl_add_u64 v[2:3], v[134:135], 1, s[24:25]
	v_readfirstlane_b32 s24, v5
	s_mov_b32 m0, s24
	s_add_u32 s24, s22, s11
	v_add_u32_e32 v5, 0x4000, v174
	v_add_u32_e32 v138, 0x20000, v136
	v_lshl_add_u64 v[2:3], v[2:3], 0, s[0:1]
	s_addc_u32 s25, s23, 0
	v_ashrrev_i32_e32 v137, 31, v136
	v_readfirstlane_b32 s11, v5
	v_add_u32_e32 v5, 0x5000, v174
	v_add_u32_e32 v140, 0x40000, v136
	global_load_lds_dwordx4 v[2:3], off
	v_lshl_add_u64 v[2:3], v[136:137], 1, s[24:25]
	s_mov_b32 m0, s11
	v_ashrrev_i32_e32 v139, 31, v138
	v_readfirstlane_b32 s11, v5
	v_add_u32_e32 v5, 0x6000, v174
	v_add_u32_e32 v142, 0x60000, v136
	global_load_lds_dwordx4 v[2:3], off
	v_lshl_add_u64 v[2:3], v[138:139], 1, s[24:25]
	s_mov_b32 m0, s11
	v_ashrrev_i32_e32 v141, 31, v140
	v_readfirstlane_b32 s11, v5
	v_add_u32_e32 v5, 0x7000, v174
	global_load_lds_dwordx4 v[2:3], off
	v_lshl_add_u64 v[2:3], v[140:141], 1, s[24:25]
	s_mov_b32 m0, s11
	v_ashrrev_i32_e32 v143, 31, v142
	v_readfirstlane_b32 s11, v5
	global_load_lds_dwordx4 v[2:3], off
	v_lshl_add_u64 v[2:3], v[142:143], 1, s[24:25]
	s_mov_b32 m0, s11
	v_lshlrev_b32_e32 v5, 1, v0
	global_load_lds_dwordx4 v[2:3], off
	v_lshrrev_b32_e32 v2, 1, v0
	v_bfe_u32 v3, v0, 1, 3
	v_and_b32_e32 v0, 3, v0
	v_and_or_b32 v0, v5, 24, v0
	v_lshlrev_b32_e32 v5, 3, v173
	v_or_b32_e32 v6, v1, v5
	v_bitop3_b32 v5, v1, v4, v5 bitop3:0x36
	v_lshlrev_b32_e32 v179, 8, v0
	v_bitop3_b32 v0, v1, v2, 7 bitop3:0x78
	s_waitcnt vmcnt(0)
	v_lshlrev_b32_e32 v175, 4, v5
	v_bitop3_b32 v5, v6, v4, 4 bitop3:0x36
	v_lshlrev_b32_e32 v180, 4, v0
	v_bitop3_b32 v0, v1, v3, 4 bitop3:0x36
	v_mov_b32_e32 v8, v119
	v_mov_b32_e32 v9, v119
	v_mov_b32_e32 v10, v119
	v_mov_b32_e32 v11, v119
	v_lshlrev_b32_e32 v176, 4, v5
	v_lshlrev_b32_e32 v177, 3, v1
	v_lshlrev_b32_e32 v178, 7, v4
	v_lshlrev_b32_e32 v181, 4, v0
	v_mov_b64_e32 v[14:15], v[10:11]
	v_mov_b64_e32 v[18:19], v[10:11]
	v_mov_b64_e32 v[22:23], v[10:11]
	v_mov_b64_e32 v[26:27], v[10:11]
	v_mov_b64_e32 v[30:31], v[10:11]
	v_mov_b64_e32 v[34:35], v[10:11]
	v_mov_b64_e32 v[38:39], v[10:11]
	v_mov_b64_e32 v[42:43], v[10:11]
	v_mov_b64_e32 v[46:47], v[10:11]
	v_mov_b64_e32 v[50:51], v[10:11]
	v_mov_b64_e32 v[54:55], v[10:11]
	v_mov_b64_e32 v[58:59], v[10:11]
	v_mov_b64_e32 v[62:63], v[10:11]
	v_mov_b64_e32 v[4:5], v[8:9]
	v_mov_b64_e32 v[0:1], v[8:9]
	s_and_b64 s[6:7], s[8:9], s[6:7]
	s_mov_b32 s24, 0
	v_mov_b32_e32 v182, 0xf149f2ca
	v_mov_b32_e32 v144, 0
	v_mov_b64_e32 v[12:13], v[8:9]
	v_mov_b64_e32 v[16:17], v[8:9]
	v_mov_b64_e32 v[20:21], v[8:9]
	v_mov_b64_e32 v[24:25], v[8:9]
	v_mov_b64_e32 v[28:29], v[8:9]
	v_mov_b64_e32 v[32:33], v[8:9]
	v_mov_b64_e32 v[36:37], v[8:9]
	v_mov_b64_e32 v[40:41], v[8:9]
	v_mov_b64_e32 v[44:45], v[8:9]
	v_mov_b64_e32 v[48:49], v[8:9]
	v_mov_b64_e32 v[52:53], v[8:9]
	v_mov_b64_e32 v[56:57], v[8:9]
	v_mov_b64_e32 v[60:61], v[8:9]
	v_mov_b64_e32 v[6:7], v[10:11]
	v_mov_b64_e32 v[2:3], v[10:11]
	v_mov_b32_e32 v145, 0
	v_mov_b32_e32 v183, 0xf149f2ca
	v_lshlrev_b32_e32 v246, 1, v128
	v_lshlrev_b32_e32 v247, 1, v130
	v_lshlrev_b32_e32 v248, 1, v132
	v_lshlrev_b32_e32 v249, 1, v134
	v_lshlrev_b32_e32 v250, 1, v136
	v_lshlrev_b32_e32 v251, 1, v138
	v_lshlrev_b32_e32 v252, 1, v140
	v_lshlrev_b32_e32 v253, 1, v142
	s_waitcnt vmcnt(0) lgkmcnt(0)
	s_barrier
	s_cmp_lg_u64 s[6:7], 0
	s_cbranch_scc1 .LBB0_822
	s_branch .LBB0_821

; __device__ __forceinline__ unsigned cvt_pk_bf16(float lo, float hi) { const f32x2_t f = {lo, hi}; return __builtin_bit_cast(unsigned, __builtin_convertvector(f, bf16x2_t)); }
; __device__ __forceinline__ f32x4 mfma16(bf16x8 a, bf16x8 b, f32x4 c) { return __builtin_amdgcn_mfma_f32_16x16x32_bf16(a, b, c, 0, 0, 0); }
; template <int KW, int VD, bool SEL> ...
;     ...
;                 for (int jj = 0; jj < 4; ++jj) { s[qt][tt][jj] = __builtin_amdgcn_exp2f(s[qt][tt][jj]); ps += s[qt][tt][jj]; }
;             lrow[qt] += ps;
; #pragma unroll
;             for (int i = 0; i < 2; ++i) {
;                 u32x4 pk;
;                 pk.x = cvt_pk_bf16(s[qt][2 * i][0], s[qt][2 * i][1]); pk.y = cvt_pk_bf16(s[qt][2 * i][2], s[qt][2 * i][3]);
;                 pk.z = cvt_pk_bf16(s[qt][2 * i + 1][0], s[qt][2 * i + 1][1]); pk.w = cvt_pk_bf16(s[qt][2 * i + 1][2], s[qt][2 * i + 1][3]);
;                 pf[qt][i] = __builtin_bit_cast(bf16x8, pk);
;             }
;         }
; #pragma unroll
;         for (int i = 0; i < 2; ++i) {
; #pragma unroll
;             for (int dt = 0; dt < VD / 16; ++dt) {
;                 const bf16x8 vf = *(const bf16x8*)(sV + (dt * 16 + fr) * 128 + ((i * 4 + fq) ^ vswz) * 16);
;                 O[0][dt] = mfma16(vf, pf[0][i], O[0][dt]);
;                 O[1][dt] = mfma16(vf, pf[1][i], O[1][dt]);
;             }
;         }
;         asm volatile("s_waitcnt vmcnt(0)" ::: "memory");
;         __syncthreads();
;         if (jn < 0) break;
;         j = jn; cur ^= 1;
;     }
;     ...
; #pragma unroll
;     for (int qt = 0; qt < 2; ++qt) { lrow[qt] += __shfl_xor(lrow[qt], 16); lrow[qt] += __shfl_xor(lrow[qt], 32); }
.LBB0_836:
	v_add_u32_e32 v194, s26, v178
	v_add_u32_e32 v195, v194, v180
	v_exp_f32_e32 v184, v108
	v_exp_f32_e32 v185, v109
	v_exp_f32_e32 v186, v110
	v_exp_f32_e32 v187, v111
	ds_read_b128 v[108:111], v195 offset:16384
	v_exp_f32_e32 v198, v100
	v_exp_f32_e32 v199, v101
	v_exp_f32_e32 v200, v102
	v_exp_f32_e32 v201, v103
	ds_read_b128 v[100:103], v195 offset:18432
	v_exp_f32_e32 v188, v104
	v_exp_f32_e32 v189, v105
	v_exp_f32_e32 v190, v106
	v_exp_f32_e32 v191, v107
	v_exp_f32_e32 v192, v96
	v_exp_f32_e32 v193, v97
	v_exp_f32_e32 v196, v98
	v_exp_f32_e32 v197, v99
	v_cvt_pk_bf16_f32 v104, v184, v185
	v_cvt_pk_bf16_f32 v105, v186, v187
	v_cvt_pk_bf16_f32 v106, v188, v189
	v_cvt_pk_bf16_f32 v107, v190, v191
	v_cvt_pk_bf16_f32 v96, v192, v193
	v_cvt_pk_bf16_f32 v97, v196, v197
	v_cvt_pk_bf16_f32 v98, v198, v199
	v_cvt_pk_bf16_f32 v99, v200, v201
	s_waitcnt lgkmcnt(1)
	s_setprio 2
	v_mfma_f32_16x16x32_bf16 v[60:63], v[108:111], v[104:107], v[60:63]
	v_exp_f32_e32 v202, v92
	v_exp_f32_e32 v203, v93
	v_exp_f32_e32 v204, v94
	v_mfma_f32_16x16x32_bf16 v[28:31], v[108:111], v[96:99], v[28:31]
	v_exp_f32_e32 v205, v95
	v_add_u32_e32 v194, v194, v181
	v_exp_f32_e32 v206, v88
	s_waitcnt lgkmcnt(0)
	v_mfma_f32_16x16x32_bf16 v[56:59], v[100:103], v[104:107], v[56:59]
	v_exp_f32_e32 v207, v89
	v_exp_f32_e32 v208, v90
	v_exp_f32_e32 v209, v91
	v_mfma_f32_16x16x32_bf16 v[24:27], v[100:103], v[96:99], v[24:27]
	ds_read_b128 v[100:103], v195 offset:20480
	ds_read_b128 v[108:111], v195 offset:22528
	ds_read_b128 v[92:95], v195 offset:28672
	v_cvt_pk_bf16_f32 v88, v202, v203
	s_waitcnt lgkmcnt(2)
	v_mfma_f32_16x16x32_bf16 v[52:55], v[100:103], v[104:107], v[52:55]
	v_cvt_pk_bf16_f32 v89, v204, v205
	v_cvt_pk_bf16_f32 v90, v206, v207
	v_cvt_pk_bf16_f32 v91, v208, v209
	v_mfma_f32_16x16x32_bf16 v[20:23], v[100:103], v[96:99], v[20:23]
	ds_read_b128 v[100:103], v195 offset:24576
	s_xor_b32 s24, s24, 1
	s_cmp_gt_i32 s25, -1
	s_waitcnt lgkmcnt(2)
	v_mfma_f32_16x16x32_bf16 v[48:51], v[108:111], v[104:107], v[48:51]
	v_mfma_f32_16x16x32_bf16 v[16:19], v[108:111], v[96:99], v[16:19]
	ds_read_b128 v[108:111], v195 offset:26624
	s_waitcnt lgkmcnt(1)
	v_mfma_f32_16x16x32_bf16 v[44:47], v[100:103], v[104:107], v[44:47]
	v_mfma_f32_16x16x32_bf16 v[12:15], v[100:103], v[96:99], v[12:15]
	ds_read_b128 v[100:103], v195 offset:30720
	s_waitcnt lgkmcnt(1)
	v_mfma_f32_16x16x32_bf16 v[40:43], v[108:111], v[104:107], v[40:43]
	v_mfma_f32_16x16x32_bf16 v[8:11], v[108:111], v[96:99], v[8:11]
	v_exp_f32_e32 v108, v80
	v_exp_f32_e32 v109, v81
	v_exp_f32_e32 v110, v82
	v_exp_f32_e32 v111, v83
	ds_read_b128 v[80:83], v194 offset:16384
	v_mfma_f32_16x16x32_bf16 v[36:39], v[92:95], v[104:107], v[36:39]
	v_mfma_f32_16x16x32_bf16 v[4:7], v[92:95], v[96:99], v[4:7]
	ds_read_b128 v[92:95], v194 offset:18432
	s_waitcnt lgkmcnt(2)
	v_mfma_f32_16x16x32_bf16 v[32:35], v[100:103], v[104:107], v[32:35]
	v_exp_f32_e32 v104, v84
	v_exp_f32_e32 v105, v85
	v_exp_f32_e32 v106, v86
	v_mfma_f32_16x16x32_bf16 v[0:3], v[100:103], v[96:99], v[0:3]
	v_exp_f32_e32 v96, v87
	v_cvt_pk_bf16_f32 v84, v108, v109
	v_cvt_pk_bf16_f32 v85, v110, v111
	v_cvt_pk_bf16_f32 v86, v104, v105
	v_cvt_pk_bf16_f32 v87, v106, v96
	s_waitcnt lgkmcnt(1)
	v_mfma_f32_16x16x32_bf16 v[60:63], v[80:83], v[88:91], v[60:63]
	v_add_f32_e32 v97, 0, v184
	v_add_f32_e32 v97, v185, v97
	v_add_f32_e32 v97, v186, v97
	v_mfma_f32_16x16x32_bf16 v[28:31], v[80:83], v[84:87], v[28:31]
	ds_read_b128 v[80:83], v194 offset:20480
	s_waitcnt lgkmcnt(1)
	v_mfma_f32_16x16x32_bf16 v[56:59], v[92:95], v[88:91], v[56:59]
	v_mfma_f32_16x16x32_bf16 v[24:27], v[92:95], v[84:87], v[24:27]
	v_add_f32_e32 v92, v187, v97
	v_add_f32_e32 v97, v188, v92
	ds_read_b128 v[92:95], v194 offset:22528
	v_add_f32_e32 v97, v189, v97
	v_add_f32_e32 v97, v190, v97
	v_add_f32_e32 v97, v191, v97
	s_waitcnt lgkmcnt(1)
	v_mfma_f32_16x16x32_bf16 v[52:55], v[80:83], v[88:91], v[52:55]
	v_mfma_f32_16x16x32_bf16 v[20:23], v[80:83], v[84:87], v[20:23]
	v_add_f32_e32 v80, v202, v97
	v_add_f32_e32 v97, v203, v80
	ds_read_b128 v[80:83], v194 offset:24576
	v_add_f32_e32 v97, v204, v97
	v_add_f32_e32 v97, v205, v97
	v_add_f32_e32 v97, v206, v97
	s_waitcnt lgkmcnt(1)
	v_mfma_f32_16x16x32_bf16 v[48:51], v[92:95], v[88:91], v[48:51]
	v_mfma_f32_16x16x32_bf16 v[16:19], v[92:95], v[84:87], v[16:19]
	v_add_f32_e32 v92, v207, v97
	v_add_f32_e32 v97, v208, v92
	ds_read_b128 v[92:95], v194 offset:26624
	v_add_f32_e32 v97, v209, v97
	v_add_f32_e32 v145, v145, v97
	v_add_f32_e32 v97, 0, v192
	s_waitcnt lgkmcnt(1)
	v_mfma_f32_16x16x32_bf16 v[44:47], v[80:83], v[88:91], v[44:47]
	v_mfma_f32_16x16x32_bf16 v[12:15], v[80:83], v[84:87], v[12:15]
	v_add_f32_e32 v80, v193, v97
	v_add_f32_e32 v97, v196, v80
	v_add_f32_e32 v97, v197, v97
	v_add_f32_e32 v97, v198, v97
	ds_read_b128 v[80:83], v194 offset:28672
	v_add_f32_e32 v97, v199, v97
	s_waitcnt lgkmcnt(1)
	v_mfma_f32_16x16x32_bf16 v[40:43], v[92:95], v[88:91], v[40:43]
	v_mfma_f32_16x16x32_bf16 v[8:11], v[92:95], v[84:87], v[8:11]
	v_add_f32_e32 v92, v200, v97
	v_add_f32_e32 v97, v201, v92
	ds_read_b128 v[92:95], v194 offset:30720
	v_add_f32_e32 v97, v108, v97
	v_add_f32_e32 v97, v109, v97
	v_add_f32_e32 v97, v110, v97
	s_waitcnt lgkmcnt(1)
	v_mfma_f32_16x16x32_bf16 v[36:39], v[80:83], v[88:91], v[36:39]
	s_waitcnt vmcnt(0)
	s_waitcnt lgkmcnt(0)
	s_barrier
	v_mfma_f32_16x16x32_bf16 v[4:7], v[80:83], v[84:87], v[4:7]
	v_add_f32_e32 v80, v111, v97
	v_add_f32_e32 v80, v104, v80
	v_add_f32_e32 v80, v105, v80
	v_mfma_f32_16x16x32_bf16 v[32:35], v[92:95], v[88:91], v[32:35]
	v_add_f32_e32 v80, v106, v80
	v_add_f32_e32 v80, v96, v80
	v_add_f32_e32 v144, v144, v80
	v_mfma_f32_16x16x32_bf16 v[0:3], v[92:95], v[84:87], v[0:3]
	s_setprio 0
	s_cbranch_scc1 .LBB0_820
	s_setprio 3
	ds_bpermute_b32 v65, v163, v145
	ds_bpermute_b32 v64, v163, v144
	s_waitcnt lgkmcnt(0)
	v_pk_add_f32 v[64:65], v[144:145], v[64:65]
	ds_bpermute_b32 v67, v162, v65
	ds_bpermute_b32 v66, v162, v64
	s_waitcnt lgkmcnt(0)
	v_pk_add_f32 v[64:65], v[64:65], v[66:67]
	s_branch .LBB0_839
